# plus P5 big-tile epilogue: all residual loads issued up front instead of 16 serial load-wait-store round trips
# baseline (speedup 1.0000x reference)
; template <class Epi>
; DEV void gemm256_tile(const bf16_t* __restrict__ A, int lda, const bf16_t* __restrict__ Bt, int ldb, int K, unsigned char* lds, const Epi& epi) {
;     ...
; #pragma unroll 4
;         for (int i = 0; i < 16; ++i) {
;             const int idx = tid + 512 * i, row = idx >> 5, cp = idx & 31, c = cp ^ (row & 31);
;             const uint4 d = *(const uint4*)(lds + row * 512 + (cp << 4));
;             *(uint4*)(epi.obase + (size_t)row * epi.old + c * 8) = epi.finish(row, c * 8, d);
;         }
;     DEV uint4 finish(int r, int c, uint4 d) const {
;         const f32x4 a = __builtin_nontemporal_load((const f32x4*)(res + (size_t)r * D + c)), b = __builtin_nontemporal_load((const f32x4*)(res + (size_t)r * D + c + 4));
;         const float r8[8] = {a[0], a[1], a[2], a[3], b[0], b[1], b[2], b[3]};
;         return add8_bf16(d, r8);
;     }
.LBB0_1005:
	v_mov_b32_e32 v23, 0
	v_mov_b32_e32 v25, 0
	v_ashrrev_i32_e32 v224, 5, v142
	v_xor_b32_e32 v4, v224, v142
	v_lshlrev_b32_e32 v4, 3, v4
	v_and_b32_e32 v143, 0xf8, v4
	v_lshlrev_b32_e32 v22, 13, v224
	v_lshl_add_u32 v22, v143, 2, v22
	v_lshl_add_u64 v[20:21], s[16:17], 0, v[22:23]
	global_load_dwordx4 v[28:31], v[20:21], off nt
	global_load_dwordx4 v[32:35], v[20:21], off offset:16 nt
	v_add_u32_e32 v3, 0x200, v142
	v_ashrrev_i32_e32 v225, 5, v3
	v_xor_b32_e32 v4, v225, v142
	v_lshlrev_b32_e32 v4, 3, v4
	v_and_b32_e32 v144, 0xf8, v4
	v_lshlrev_b32_e32 v22, 13, v225
	v_lshl_add_u32 v22, v144, 2, v22
	v_lshl_add_u64 v[20:21], s[16:17], 0, v[22:23]
	global_load_dwordx4 v[36:39], v[20:21], off nt
	global_load_dwordx4 v[40:43], v[20:21], off offset:16 nt
	v_add_u32_e32 v3, 0x400, v142
	v_ashrrev_i32_e32 v226, 5, v3
	v_xor_b32_e32 v4, v226, v142
	v_lshlrev_b32_e32 v4, 3, v4
	v_and_b32_e32 v145, 0xf8, v4
	v_lshlrev_b32_e32 v22, 13, v226
	v_lshl_add_u32 v22, v145, 2, v22
	v_lshl_add_u64 v[20:21], s[16:17], 0, v[22:23]
	global_load_dwordx4 v[44:47], v[20:21], off nt
	global_load_dwordx4 v[48:51], v[20:21], off offset:16 nt
	v_add_u32_e32 v3, 0x600, v142
	v_ashrrev_i32_e32 v227, 5, v3
	v_xor_b32_e32 v4, v227, v142
	v_lshlrev_b32_e32 v4, 3, v4
	v_and_b32_e32 v146, 0xf8, v4
	v_lshlrev_b32_e32 v22, 13, v227
	v_lshl_add_u32 v22, v146, 2, v22
	v_lshl_add_u64 v[20:21], s[16:17], 0, v[22:23]
	global_load_dwordx4 v[52:55], v[20:21], off nt
	global_load_dwordx4 v[56:59], v[20:21], off offset:16 nt
	v_add_u32_e32 v3, 0x800, v142
	v_ashrrev_i32_e32 v228, 5, v3
	v_xor_b32_e32 v4, v228, v142
	v_lshlrev_b32_e32 v4, 3, v4
	v_and_b32_e32 v147, 0xf8, v4
	v_lshlrev_b32_e32 v22, 13, v228
	v_lshl_add_u32 v22, v147, 2, v22
	v_lshl_add_u64 v[20:21], s[16:17], 0, v[22:23]
	global_load_dwordx4 v[60:63], v[20:21], off nt
	global_load_dwordx4 v[64:67], v[20:21], off offset:16 nt
	v_add_u32_e32 v3, 0xa00, v142
	v_ashrrev_i32_e32 v229, 5, v3
	v_xor_b32_e32 v4, v229, v142
	v_lshlrev_b32_e32 v4, 3, v4
	v_and_b32_e32 v148, 0xf8, v4
	v_lshlrev_b32_e32 v22, 13, v229
	v_lshl_add_u32 v22, v148, 2, v22
	v_lshl_add_u64 v[20:21], s[16:17], 0, v[22:23]
	global_load_dwordx4 v[68:71], v[20:21], off nt
	global_load_dwordx4 v[72:75], v[20:21], off offset:16 nt
	v_add_u32_e32 v3, 0xc00, v142
	v_ashrrev_i32_e32 v230, 5, v3
	v_xor_b32_e32 v4, v230, v142
	v_lshlrev_b32_e32 v4, 3, v4
	v_and_b32_e32 v149, 0xf8, v4
	v_lshlrev_b32_e32 v22, 13, v230
	v_lshl_add_u32 v22, v149, 2, v22
	v_lshl_add_u64 v[20:21], s[16:17], 0, v[22:23]
	global_load_dwordx4 v[76:79], v[20:21], off nt
	global_load_dwordx4 v[80:83], v[20:21], off offset:16 nt
	v_add_u32_e32 v3, 0xe00, v142
	v_ashrrev_i32_e32 v231, 5, v3
	v_xor_b32_e32 v4, v231, v142
	v_lshlrev_b32_e32 v4, 3, v4
	v_and_b32_e32 v150, 0xf8, v4
	v_lshlrev_b32_e32 v22, 13, v231
	v_lshl_add_u32 v22, v150, 2, v22
	v_lshl_add_u64 v[20:21], s[16:17], 0, v[22:23]
	global_load_dwordx4 v[84:87], v[20:21], off nt
	global_load_dwordx4 v[88:91], v[20:21], off offset:16 nt
	v_add_u32_e32 v3, 0x1000, v142
	v_ashrrev_i32_e32 v232, 5, v3
	v_xor_b32_e32 v4, v232, v142
	v_lshlrev_b32_e32 v4, 3, v4
	v_and_b32_e32 v151, 0xf8, v4
	v_lshlrev_b32_e32 v22, 13, v232
	v_lshl_add_u32 v22, v151, 2, v22
	v_lshl_add_u64 v[20:21], s[16:17], 0, v[22:23]
	global_load_dwordx4 v[92:95], v[20:21], off nt
	global_load_dwordx4 v[96:99], v[20:21], off offset:16 nt
	v_add_u32_e32 v3, 0x1200, v142
	v_ashrrev_i32_e32 v233, 5, v3
	v_xor_b32_e32 v4, v233, v142
	v_lshlrev_b32_e32 v4, 3, v4
	v_and_b32_e32 v152, 0xf8, v4
	v_lshlrev_b32_e32 v22, 13, v233
	v_lshl_add_u32 v22, v152, 2, v22
	v_lshl_add_u64 v[20:21], s[16:17], 0, v[22:23]
	global_load_dwordx4 v[100:103], v[20:21], off nt
	global_load_dwordx4 v[104:107], v[20:21], off offset:16 nt
	v_add_u32_e32 v3, 0x1400, v142
	v_ashrrev_i32_e32 v234, 5, v3
	v_xor_b32_e32 v4, v234, v142
	v_lshlrev_b32_e32 v4, 3, v4
	v_and_b32_e32 v153, 0xf8, v4
	v_lshlrev_b32_e32 v22, 13, v234
	v_lshl_add_u32 v22, v153, 2, v22
	v_lshl_add_u64 v[20:21], s[16:17], 0, v[22:23]
	global_load_dwordx4 v[108:111], v[20:21], off nt
	global_load_dwordx4 v[112:115], v[20:21], off offset:16 nt
	v_add_u32_e32 v3, 0x1600, v142
	v_ashrrev_i32_e32 v235, 5, v3
	v_xor_b32_e32 v4, v235, v142
	v_lshlrev_b32_e32 v4, 3, v4
	v_and_b32_e32 v154, 0xf8, v4
	v_lshlrev_b32_e32 v22, 13, v235
	v_lshl_add_u32 v22, v154, 2, v22
	v_lshl_add_u64 v[20:21], s[16:17], 0, v[22:23]
	global_load_dwordx4 v[116:119], v[20:21], off nt
	global_load_dwordx4 v[120:123], v[20:21], off offset:16 nt
	v_add_u32_e32 v3, 0x1800, v142
	v_ashrrev_i32_e32 v236, 5, v3
	v_xor_b32_e32 v4, v236, v142
	v_lshlrev_b32_e32 v4, 3, v4
	v_and_b32_e32 v155, 0xf8, v4
	v_lshlrev_b32_e32 v22, 13, v236
	v_lshl_add_u32 v22, v155, 2, v22
	v_lshl_add_u64 v[20:21], s[16:17], 0, v[22:23]
	global_load_dwordx4 v[192:195], v[20:21], off nt
	global_load_dwordx4 v[196:199], v[20:21], off offset:16 nt
	v_add_u32_e32 v3, 0x1a00, v142
	v_ashrrev_i32_e32 v237, 5, v3
	v_xor_b32_e32 v4, v237, v142
	v_lshlrev_b32_e32 v4, 3, v4
	v_and_b32_e32 v156, 0xf8, v4
	v_lshlrev_b32_e32 v22, 13, v237
	v_lshl_add_u32 v22, v156, 2, v22
	v_lshl_add_u64 v[20:21], s[16:17], 0, v[22:23]
	global_load_dwordx4 v[200:203], v[20:21], off nt
	global_load_dwordx4 v[204:207], v[20:21], off offset:16 nt
	v_add_u32_e32 v3, 0x1c00, v142
	v_ashrrev_i32_e32 v238, 5, v3
	v_xor_b32_e32 v4, v238, v142
	v_lshlrev_b32_e32 v4, 3, v4
	v_and_b32_e32 v157, 0xf8, v4
	v_lshlrev_b32_e32 v22, 13, v238
	v_lshl_add_u32 v22, v157, 2, v22
	v_lshl_add_u64 v[20:21], s[16:17], 0, v[22:23]
	global_load_dwordx4 v[208:211], v[20:21], off nt
	global_load_dwordx4 v[212:215], v[20:21], off offset:16 nt
	v_add_u32_e32 v3, 0x1e00, v142
	v_ashrrev_i32_e32 v239, 5, v3
	v_xor_b32_e32 v4, v239, v142
	v_lshlrev_b32_e32 v4, 3, v4
	v_and_b32_e32 v172, 0xf8, v4
	v_lshlrev_b32_e32 v22, 13, v239
	v_lshl_add_u32 v22, v172, 2, v22
	v_lshl_add_u64 v[20:21], s[16:17], 0, v[22:23]
	global_load_dwordx4 v[216:219], v[20:21], off nt
	global_load_dwordx4 v[220:223], v[20:21], off offset:16 nt
	v_lshl_or_b32 v5, v224, 9, v2
	ds_read_b128 v[8:11], v5
	v_lshl_or_b32 v5, v225, 9, v2
	ds_read_b128 v[12:15], v5
	v_mad_i64_i32 v[20:21], s[24:25], v224, s21, v[26:27]
	v_lshlrev_b32_e32 v24, 1, v143
	v_lshl_add_u64 v[20:21], v[20:21], 0, v[24:25]
	s_waitcnt lgkmcnt(1)
; DEV unsigned cvt_pk_bf16(float lo, float hi) { const f32x2_t v = {lo, hi}; const bf16x2_t b = __builtin_convertvector(v, bf16x2_t); return __builtin_bit_cast(unsigned, b); }
; DEV float bflo(unsigned u) { return __uint_as_float(u << 16); }
; DEV float bfhi(unsigned u) { return __uint_as_float(u & 0xffff0000u); }
; template <class Epi>
; DEV void gemm256_tile(const bf16_t* __restrict__ A, int lda, const bf16_t* __restrict__ Bt, int ldb, int K, unsigned char* lds, const Epi& epi) {
;     ...
;         for (int i = 0; i < 16; ++i) {
;             const int idx = tid + 512 * i, row = idx >> 5, cp = idx & 31, c = cp ^ (row & 31);
;             const uint4 d = *(const uint4*)(lds + row * 512 + (cp << 4));
;             *(uint4*)(epi.obase + (size_t)row * epi.old + c * 8) = epi.finish(row, c * 8, d);
;         }
; DEV uint4 add8_bf16(uint4 d, const float* r8) {
;     uint4 o; o.x = cvt_pk_bf16(bflo(d.x) + r8[0], bfhi(d.x) + r8[1]); o.y = cvt_pk_bf16(bflo(d.y) + r8[2], bfhi(d.y) + r8[3]);
;     o.z = cvt_pk_bf16(bflo(d.z) + r8[4], bfhi(d.z) + r8[5]); o.w = cvt_pk_bf16(bflo(d.w) + r8[6], bfhi(d.w) + r8[7]); return o;
; }
;     DEV uint4 finish(int r, int c, uint4 d) const {
;         const f32x4 a = __builtin_nontemporal_load((const f32x4*)(res + (size_t)r * D + c)), b = __builtin_nontemporal_load((const f32x4*)(res + (size_t)r * D + c + 4));
;         const float r8[8] = {a[0], a[1], a[2], a[3], b[0], b[1], b[2], b[3]};
;         return add8_bf16(d, r8);
;     }
	v_lshlrev_b32_e32 v16, 16, v8
	v_and_b32_e32 v17, 0xffff0000, v8
	v_lshlrev_b32_e32 v18, 16, v9
	v_and_b32_e32 v19, 0xffff0000, v9
	v_lshlrev_b32_e32 v6, 16, v10
	v_and_b32_e32 v7, 0xffff0000, v10
	v_lshlrev_b32_e32 v22, 16, v11
	v_and_b32_e32 v23, 0xffff0000, v11
	s_waitcnt vmcnt(30)
	v_pk_add_f32 v[28:29], v[28:29], v[16:17]
	v_pk_add_f32 v[30:31], v[30:31], v[18:19]
	v_pk_add_f32 v[32:33], v[32:33], v[6:7]
	v_pk_add_f32 v[34:35], v[34:35], v[22:23]
	v_cvt_pk_bf16_f32 v28, v28, v29
	v_cvt_pk_bf16_f32 v29, v30, v31
	v_cvt_pk_bf16_f32 v30, v32, v33
	v_cvt_pk_bf16_f32 v31, v34, v35
	global_store_dwordx4 v[20:21], v[28:31], off
	v_lshl_or_b32 v5, v226, 9, v2
	ds_read_b128 v[8:11], v5
	v_mad_i64_i32 v[20:21], s[24:25], v225, s21, v[26:27]
	v_lshlrev_b32_e32 v24, 1, v144
	v_lshl_add_u64 v[20:21], v[20:21], 0, v[24:25]
	s_waitcnt lgkmcnt(1)
	v_lshlrev_b32_e32 v16, 16, v12
	v_and_b32_e32 v17, 0xffff0000, v12
	v_lshlrev_b32_e32 v18, 16, v13
	v_and_b32_e32 v19, 0xffff0000, v13
	v_lshlrev_b32_e32 v6, 16, v14
	v_and_b32_e32 v7, 0xffff0000, v14
	v_lshlrev_b32_e32 v22, 16, v15
	v_and_b32_e32 v23, 0xffff0000, v15
	s_waitcnt vmcnt(29)
	v_pk_add_f32 v[36:37], v[36:37], v[16:17]
	v_pk_add_f32 v[38:39], v[38:39], v[18:19]
	v_pk_add_f32 v[40:41], v[40:41], v[6:7]
	v_pk_add_f32 v[42:43], v[42:43], v[22:23]
	v_cvt_pk_bf16_f32 v36, v36, v37
	v_cvt_pk_bf16_f32 v37, v38, v39
	v_cvt_pk_bf16_f32 v38, v40, v41
	v_cvt_pk_bf16_f32 v39, v42, v43
	global_store_dwordx4 v[20:21], v[36:39], off
	v_lshl_or_b32 v5, v227, 9, v2
	ds_read_b128 v[12:15], v5
	v_mad_i64_i32 v[20:21], s[24:25], v226, s21, v[26:27]
	v_lshlrev_b32_e32 v24, 1, v145
	v_lshl_add_u64 v[20:21], v[20:21], 0, v[24:25]
	s_waitcnt lgkmcnt(1)
	v_lshlrev_b32_e32 v16, 16, v8
	v_and_b32_e32 v17, 0xffff0000, v8
	v_lshlrev_b32_e32 v18, 16, v9
	v_and_b32_e32 v19, 0xffff0000, v9
	v_lshlrev_b32_e32 v6, 16, v10
	v_and_b32_e32 v7, 0xffff0000, v10
	v_lshlrev_b32_e32 v22, 16, v11
	v_and_b32_e32 v23, 0xffff0000, v11
	s_waitcnt vmcnt(28)
	v_pk_add_f32 v[44:45], v[44:45], v[16:17]
	v_pk_add_f32 v[46:47], v[46:47], v[18:19]
	v_pk_add_f32 v[48:49], v[48:49], v[6:7]
	v_pk_add_f32 v[50:51], v[50:51], v[22:23]
	v_cvt_pk_bf16_f32 v44, v44, v45
	v_cvt_pk_bf16_f32 v45, v46, v47
	v_cvt_pk_bf16_f32 v46, v48, v49
	v_cvt_pk_bf16_f32 v47, v50, v51
	global_store_dwordx4 v[20:21], v[44:47], off
	v_lshl_or_b32 v5, v228, 9, v2
	ds_read_b128 v[8:11], v5
	v_mad_i64_i32 v[20:21], s[24:25], v227, s21, v[26:27]
	v_lshlrev_b32_e32 v24, 1, v146
	v_lshl_add_u64 v[20:21], v[20:21], 0, v[24:25]
	s_waitcnt lgkmcnt(1)
	v_lshlrev_b32_e32 v16, 16, v12
	v_and_b32_e32 v17, 0xffff0000, v12
	v_lshlrev_b32_e32 v18, 16, v13
	v_and_b32_e32 v19, 0xffff0000, v13
	v_lshlrev_b32_e32 v6, 16, v14
	v_and_b32_e32 v7, 0xffff0000, v14
	v_lshlrev_b32_e32 v22, 16, v15
	v_and_b32_e32 v23, 0xffff0000, v15
	s_waitcnt vmcnt(27)
	v_pk_add_f32 v[52:53], v[52:53], v[16:17]
	v_pk_add_f32 v[54:55], v[54:55], v[18:19]
	v_pk_add_f32 v[56:57], v[56:57], v[6:7]
	v_pk_add_f32 v[58:59], v[58:59], v[22:23]
	v_cvt_pk_bf16_f32 v52, v52, v53
	v_cvt_pk_bf16_f32 v53, v54, v55
	v_cvt_pk_bf16_f32 v54, v56, v57
	v_cvt_pk_bf16_f32 v55, v58, v59
	global_store_dwordx4 v[20:21], v[52:55], off
	v_lshl_or_b32 v5, v229, 9, v2
	ds_read_b128 v[12:15], v5
	v_mad_i64_i32 v[20:21], s[24:25], v228, s21, v[26:27]
	v_lshlrev_b32_e32 v24, 1, v147
	v_lshl_add_u64 v[20:21], v[20:21], 0, v[24:25]
	s_waitcnt lgkmcnt(1)
	v_lshlrev_b32_e32 v16, 16, v8
	v_and_b32_e32 v17, 0xffff0000, v8
	v_lshlrev_b32_e32 v18, 16, v9
	v_and_b32_e32 v19, 0xffff0000, v9
	v_lshlrev_b32_e32 v6, 16, v10
	v_and_b32_e32 v7, 0xffff0000, v10
	v_lshlrev_b32_e32 v22, 16, v11
	v_and_b32_e32 v23, 0xffff0000, v11
	s_waitcnt vmcnt(26)
	v_pk_add_f32 v[60:61], v[60:61], v[16:17]
	v_pk_add_f32 v[62:63], v[62:63], v[18:19]
	v_pk_add_f32 v[64:65], v[64:65], v[6:7]
	v_pk_add_f32 v[66:67], v[66:67], v[22:23]
	v_cvt_pk_bf16_f32 v60, v60, v61
	v_cvt_pk_bf16_f32 v61, v62, v63
	v_cvt_pk_bf16_f32 v62, v64, v65
	v_cvt_pk_bf16_f32 v63, v66, v67
	global_store_dwordx4 v[20:21], v[60:63], off
	v_lshl_or_b32 v5, v230, 9, v2
	ds_read_b128 v[8:11], v5
	v_mad_i64_i32 v[20:21], s[24:25], v229, s21, v[26:27]
	v_lshlrev_b32_e32 v24, 1, v148
	v_lshl_add_u64 v[20:21], v[20:21], 0, v[24:25]
	s_waitcnt lgkmcnt(1)
	v_lshlrev_b32_e32 v16, 16, v12
	v_and_b32_e32 v17, 0xffff0000, v12
	v_lshlrev_b32_e32 v18, 16, v13
	v_and_b32_e32 v19, 0xffff0000, v13
	v_lshlrev_b32_e32 v6, 16, v14
	v_and_b32_e32 v7, 0xffff0000, v14
	v_lshlrev_b32_e32 v22, 16, v15
	v_and_b32_e32 v23, 0xffff0000, v15
	s_waitcnt vmcnt(25)
	v_pk_add_f32 v[68:69], v[68:69], v[16:17]
	v_pk_add_f32 v[70:71], v[70:71], v[18:19]
	v_pk_add_f32 v[72:73], v[72:73], v[6:7]
	v_pk_add_f32 v[74:75], v[74:75], v[22:23]
	v_cvt_pk_bf16_f32 v68, v68, v69
	v_cvt_pk_bf16_f32 v69, v70, v71
	v_cvt_pk_bf16_f32 v70, v72, v73
	v_cvt_pk_bf16_f32 v71, v74, v75
	global_store_dwordx4 v[20:21], v[68:71], off
	v_lshl_or_b32 v5, v231, 9, v2
	ds_read_b128 v[12:15], v5
	v_mad_i64_i32 v[20:21], s[24:25], v230, s21, v[26:27]
	v_lshlrev_b32_e32 v24, 1, v149
	v_lshl_add_u64 v[20:21], v[20:21], 0, v[24:25]
	s_waitcnt lgkmcnt(1)
	v_lshlrev_b32_e32 v16, 16, v8
	v_and_b32_e32 v17, 0xffff0000, v8
	v_lshlrev_b32_e32 v18, 16, v9
	v_and_b32_e32 v19, 0xffff0000, v9
	v_lshlrev_b32_e32 v6, 16, v10
	v_and_b32_e32 v7, 0xffff0000, v10
	v_lshlrev_b32_e32 v22, 16, v11
	v_and_b32_e32 v23, 0xffff0000, v11
	s_waitcnt vmcnt(24)
; DEV unsigned cvt_pk_bf16(float lo, float hi) { const f32x2_t v = {lo, hi}; const bf16x2_t b = __builtin_convertvector(v, bf16x2_t); return __builtin_bit_cast(unsigned, b); }
; DEV float bflo(unsigned u) { return __uint_as_float(u << 16); }
; DEV float bfhi(unsigned u) { return __uint_as_float(u & 0xffff0000u); }
; template <class Epi>
; DEV void gemm256_tile(const bf16_t* __restrict__ A, int lda, const bf16_t* __restrict__ Bt, int ldb, int K, unsigned char* lds, const Epi& epi) {
;     ...
;         for (int i = 0; i < 16; ++i) {
;             const int idx = tid + 512 * i, row = idx >> 5, cp = idx & 31, c = cp ^ (row & 31);
;             const uint4 d = *(const uint4*)(lds + row * 512 + (cp << 4));
;             *(uint4*)(epi.obase + (size_t)row * epi.old + c * 8) = epi.finish(row, c * 8, d);
;         }
; DEV uint4 add8_bf16(uint4 d, const float* r8) {
;     uint4 o; o.x = cvt_pk_bf16(bflo(d.x) + r8[0], bfhi(d.x) + r8[1]); o.y = cvt_pk_bf16(bflo(d.y) + r8[2], bfhi(d.y) + r8[3]);
;     o.z = cvt_pk_bf16(bflo(d.z) + r8[4], bfhi(d.z) + r8[5]); o.w = cvt_pk_bf16(bflo(d.w) + r8[6], bfhi(d.w) + r8[7]); return o;
; }
;     DEV uint4 finish(int r, int c, uint4 d) const {
;         const f32x4 a = __builtin_nontemporal_load((const f32x4*)(res + (size_t)r * D + c)), b = __builtin_nontemporal_load((const f32x4*)(res + (size_t)r * D + c + 4));
;         const float r8[8] = {a[0], a[1], a[2], a[3], b[0], b[1], b[2], b[3]};
;         return add8_bf16(d, r8);
;     }
	v_pk_add_f32 v[76:77], v[76:77], v[16:17]
	v_pk_add_f32 v[78:79], v[78:79], v[18:19]
	v_pk_add_f32 v[80:81], v[80:81], v[6:7]
	v_pk_add_f32 v[82:83], v[82:83], v[22:23]
	v_cvt_pk_bf16_f32 v76, v76, v77
	v_cvt_pk_bf16_f32 v77, v78, v79
	v_cvt_pk_bf16_f32 v78, v80, v81
	v_cvt_pk_bf16_f32 v79, v82, v83
	global_store_dwordx4 v[20:21], v[76:79], off
	v_lshl_or_b32 v5, v232, 9, v2
	ds_read_b128 v[8:11], v5
	v_mad_i64_i32 v[20:21], s[24:25], v231, s21, v[26:27]
	v_lshlrev_b32_e32 v24, 1, v150
	v_lshl_add_u64 v[20:21], v[20:21], 0, v[24:25]
	s_waitcnt lgkmcnt(1)
	v_lshlrev_b32_e32 v16, 16, v12
	v_and_b32_e32 v17, 0xffff0000, v12
	v_lshlrev_b32_e32 v18, 16, v13
	v_and_b32_e32 v19, 0xffff0000, v13
	v_lshlrev_b32_e32 v6, 16, v14
	v_and_b32_e32 v7, 0xffff0000, v14
	v_lshlrev_b32_e32 v22, 16, v15
	v_and_b32_e32 v23, 0xffff0000, v15
	s_waitcnt vmcnt(23)
	v_pk_add_f32 v[84:85], v[84:85], v[16:17]
	v_pk_add_f32 v[86:87], v[86:87], v[18:19]
	v_pk_add_f32 v[88:89], v[88:89], v[6:7]
	v_pk_add_f32 v[90:91], v[90:91], v[22:23]
	v_cvt_pk_bf16_f32 v84, v84, v85
	v_cvt_pk_bf16_f32 v85, v86, v87
	v_cvt_pk_bf16_f32 v86, v88, v89
	v_cvt_pk_bf16_f32 v87, v90, v91
	global_store_dwordx4 v[20:21], v[84:87], off
	v_lshl_or_b32 v5, v233, 9, v2
	ds_read_b128 v[12:15], v5
	v_mad_i64_i32 v[20:21], s[24:25], v232, s21, v[26:27]
	v_lshlrev_b32_e32 v24, 1, v151
	v_lshl_add_u64 v[20:21], v[20:21], 0, v[24:25]
	s_waitcnt lgkmcnt(1)
	v_lshlrev_b32_e32 v16, 16, v8
	v_and_b32_e32 v17, 0xffff0000, v8
	v_lshlrev_b32_e32 v18, 16, v9
	v_and_b32_e32 v19, 0xffff0000, v9
	v_lshlrev_b32_e32 v6, 16, v10
	v_and_b32_e32 v7, 0xffff0000, v10
	v_lshlrev_b32_e32 v22, 16, v11
	v_and_b32_e32 v23, 0xffff0000, v11
	s_waitcnt vmcnt(22)
	v_pk_add_f32 v[92:93], v[92:93], v[16:17]
	v_pk_add_f32 v[94:95], v[94:95], v[18:19]
	v_pk_add_f32 v[96:97], v[96:97], v[6:7]
	v_pk_add_f32 v[98:99], v[98:99], v[22:23]
	v_cvt_pk_bf16_f32 v92, v92, v93
	v_cvt_pk_bf16_f32 v93, v94, v95
	v_cvt_pk_bf16_f32 v94, v96, v97
	v_cvt_pk_bf16_f32 v95, v98, v99
	global_store_dwordx4 v[20:21], v[92:95], off
	v_lshl_or_b32 v5, v234, 9, v2
	ds_read_b128 v[8:11], v5
	v_mad_i64_i32 v[20:21], s[24:25], v233, s21, v[26:27]
	v_lshlrev_b32_e32 v24, 1, v152
	v_lshl_add_u64 v[20:21], v[20:21], 0, v[24:25]
	s_waitcnt lgkmcnt(1)
	v_lshlrev_b32_e32 v16, 16, v12
	v_and_b32_e32 v17, 0xffff0000, v12
	v_lshlrev_b32_e32 v18, 16, v13
	v_and_b32_e32 v19, 0xffff0000, v13
	v_lshlrev_b32_e32 v6, 16, v14
	v_and_b32_e32 v7, 0xffff0000, v14
	v_lshlrev_b32_e32 v22, 16, v15
	v_and_b32_e32 v23, 0xffff0000, v15
	s_waitcnt vmcnt(21)
	v_pk_add_f32 v[100:101], v[100:101], v[16:17]
	v_pk_add_f32 v[102:103], v[102:103], v[18:19]
	v_pk_add_f32 v[104:105], v[104:105], v[6:7]
	v_pk_add_f32 v[106:107], v[106:107], v[22:23]
	v_cvt_pk_bf16_f32 v100, v100, v101
	v_cvt_pk_bf16_f32 v101, v102, v103
	v_cvt_pk_bf16_f32 v102, v104, v105
	v_cvt_pk_bf16_f32 v103, v106, v107
	global_store_dwordx4 v[20:21], v[100:103], off
	v_lshl_or_b32 v5, v235, 9, v2
	ds_read_b128 v[12:15], v5
	v_mad_i64_i32 v[20:21], s[24:25], v234, s21, v[26:27]
	v_lshlrev_b32_e32 v24, 1, v153
	v_lshl_add_u64 v[20:21], v[20:21], 0, v[24:25]
	s_waitcnt lgkmcnt(1)
	v_lshlrev_b32_e32 v16, 16, v8
	v_and_b32_e32 v17, 0xffff0000, v8
	v_lshlrev_b32_e32 v18, 16, v9
	v_and_b32_e32 v19, 0xffff0000, v9
	v_lshlrev_b32_e32 v6, 16, v10
	v_and_b32_e32 v7, 0xffff0000, v10
	v_lshlrev_b32_e32 v22, 16, v11
	v_and_b32_e32 v23, 0xffff0000, v11
	s_waitcnt vmcnt(20)
	v_pk_add_f32 v[108:109], v[108:109], v[16:17]
	v_pk_add_f32 v[110:111], v[110:111], v[18:19]
	v_pk_add_f32 v[112:113], v[112:113], v[6:7]
	v_pk_add_f32 v[114:115], v[114:115], v[22:23]
	v_cvt_pk_bf16_f32 v108, v108, v109
	v_cvt_pk_bf16_f32 v109, v110, v111
	v_cvt_pk_bf16_f32 v110, v112, v113
	v_cvt_pk_bf16_f32 v111, v114, v115
	global_store_dwordx4 v[20:21], v[108:111], off
	v_lshl_or_b32 v5, v236, 9, v2
	ds_read_b128 v[8:11], v5
	v_mad_i64_i32 v[20:21], s[24:25], v235, s21, v[26:27]
	v_lshlrev_b32_e32 v24, 1, v154
	v_lshl_add_u64 v[20:21], v[20:21], 0, v[24:25]
	s_waitcnt lgkmcnt(1)
; template <class Epi>
; DEV void gemm256_tile(const bf16_t* __restrict__ A, int lda, const bf16_t* __restrict__ Bt, int ldb, int K, unsigned char* lds, const Epi& epi) {
;     ...
;         for (int i = 0; i < 16; ++i) {
;             const int idx = tid + 512 * i, row = idx >> 5, cp = idx & 31, c = cp ^ (row & 31);
;             const uint4 d = *(const uint4*)(lds + row * 512 + (cp << 4));
;             *(uint4*)(epi.obase + (size_t)row * epi.old + c * 8) = epi.finish(row, c * 8, d);
;         }
;         __syncthreads();
; __global__ void __launch_bounds__(512) hymba_fwd(Params p) {
;     ...
;         for (int t = bid; t < 32 * 8; t += G) { int nt, mt; tile_map(t, 32, 8, mt, nt);
;             EpiResidS e{p.in[0] + (size_t)mt * 256 * D + nt * 256, x1 + (size_t)mt * 256 * LDB + nt * 256, LDB};
;             gemm256_tile(mix + (size_t)mt * 256 * LDB, LDB, Wt_out + (size_t)nt * 256 * LDB, LDB, D, lds, e);
;         }
	v_lshlrev_b32_e32 v16, 16, v12
	v_and_b32_e32 v17, 0xffff0000, v12
	v_lshlrev_b32_e32 v18, 16, v13
	v_and_b32_e32 v19, 0xffff0000, v13
	v_lshlrev_b32_e32 v6, 16, v14
	v_and_b32_e32 v7, 0xffff0000, v14
	v_lshlrev_b32_e32 v22, 16, v15
	v_and_b32_e32 v23, 0xffff0000, v15
	s_waitcnt vmcnt(19)
	v_pk_add_f32 v[116:117], v[116:117], v[16:17]
	v_pk_add_f32 v[118:119], v[118:119], v[18:19]
	v_pk_add_f32 v[120:121], v[120:121], v[6:7]
	v_pk_add_f32 v[122:123], v[122:123], v[22:23]
	v_cvt_pk_bf16_f32 v116, v116, v117
	v_cvt_pk_bf16_f32 v117, v118, v119
	v_cvt_pk_bf16_f32 v118, v120, v121
	v_cvt_pk_bf16_f32 v119, v122, v123
	global_store_dwordx4 v[20:21], v[116:119], off
	v_lshl_or_b32 v5, v237, 9, v2
	ds_read_b128 v[12:15], v5
	v_mad_i64_i32 v[20:21], s[24:25], v236, s21, v[26:27]
	v_lshlrev_b32_e32 v24, 1, v155
	v_lshl_add_u64 v[20:21], v[20:21], 0, v[24:25]
	s_waitcnt lgkmcnt(1)
	v_lshlrev_b32_e32 v16, 16, v8
	v_and_b32_e32 v17, 0xffff0000, v8
	v_lshlrev_b32_e32 v18, 16, v9
	v_and_b32_e32 v19, 0xffff0000, v9
	v_lshlrev_b32_e32 v6, 16, v10
	v_and_b32_e32 v7, 0xffff0000, v10
	v_lshlrev_b32_e32 v22, 16, v11
	v_and_b32_e32 v23, 0xffff0000, v11
	s_waitcnt vmcnt(18)
	v_pk_add_f32 v[192:193], v[192:193], v[16:17]
	v_pk_add_f32 v[194:195], v[194:195], v[18:19]
	v_pk_add_f32 v[196:197], v[196:197], v[6:7]
	v_pk_add_f32 v[198:199], v[198:199], v[22:23]
	v_cvt_pk_bf16_f32 v192, v192, v193
	v_cvt_pk_bf16_f32 v193, v194, v195
	v_cvt_pk_bf16_f32 v194, v196, v197
	v_cvt_pk_bf16_f32 v195, v198, v199
	global_store_dwordx4 v[20:21], v[192:195], off
	v_lshl_or_b32 v5, v238, 9, v2
	ds_read_b128 v[8:11], v5
	v_mad_i64_i32 v[20:21], s[24:25], v237, s21, v[26:27]
	v_lshlrev_b32_e32 v24, 1, v156
	v_lshl_add_u64 v[20:21], v[20:21], 0, v[24:25]
	s_waitcnt lgkmcnt(1)
	v_lshlrev_b32_e32 v16, 16, v12
	v_and_b32_e32 v17, 0xffff0000, v12
	v_lshlrev_b32_e32 v18, 16, v13
	v_and_b32_e32 v19, 0xffff0000, v13
	v_lshlrev_b32_e32 v6, 16, v14
	v_and_b32_e32 v7, 0xffff0000, v14
	v_lshlrev_b32_e32 v22, 16, v15
	v_and_b32_e32 v23, 0xffff0000, v15
	s_waitcnt vmcnt(17)
	v_pk_add_f32 v[200:201], v[200:201], v[16:17]
	v_pk_add_f32 v[202:203], v[202:203], v[18:19]
	v_pk_add_f32 v[204:205], v[204:205], v[6:7]
	v_pk_add_f32 v[206:207], v[206:207], v[22:23]
	v_cvt_pk_bf16_f32 v200, v200, v201
	v_cvt_pk_bf16_f32 v201, v202, v203
	v_cvt_pk_bf16_f32 v202, v204, v205
	v_cvt_pk_bf16_f32 v203, v206, v207
	global_store_dwordx4 v[20:21], v[200:203], off
	v_lshl_or_b32 v5, v239, 9, v2
	ds_read_b128 v[12:15], v5
	v_mad_i64_i32 v[20:21], s[24:25], v238, s21, v[26:27]
	v_lshlrev_b32_e32 v24, 1, v157
	v_lshl_add_u64 v[20:21], v[20:21], 0, v[24:25]
	s_waitcnt lgkmcnt(1)
	v_lshlrev_b32_e32 v16, 16, v8
	v_and_b32_e32 v17, 0xffff0000, v8
	v_lshlrev_b32_e32 v18, 16, v9
	v_and_b32_e32 v19, 0xffff0000, v9
	v_lshlrev_b32_e32 v6, 16, v10
	v_and_b32_e32 v7, 0xffff0000, v10
	v_lshlrev_b32_e32 v22, 16, v11
	v_and_b32_e32 v23, 0xffff0000, v11
	s_waitcnt vmcnt(16)
	v_pk_add_f32 v[208:209], v[208:209], v[16:17]
	v_pk_add_f32 v[210:211], v[210:211], v[18:19]
	v_pk_add_f32 v[212:213], v[212:213], v[6:7]
	v_pk_add_f32 v[214:215], v[214:215], v[22:23]
	v_cvt_pk_bf16_f32 v208, v208, v209
	v_cvt_pk_bf16_f32 v209, v210, v211
	v_cvt_pk_bf16_f32 v210, v212, v213
	v_cvt_pk_bf16_f32 v211, v214, v215
	global_store_dwordx4 v[20:21], v[208:211], off
	v_mad_i64_i32 v[20:21], s[24:25], v239, s21, v[26:27]
	v_lshlrev_b32_e32 v24, 1, v172
	v_lshl_add_u64 v[20:21], v[20:21], 0, v[24:25]
	s_waitcnt lgkmcnt(0)
	v_lshlrev_b32_e32 v16, 16, v12
	v_and_b32_e32 v17, 0xffff0000, v12
	v_lshlrev_b32_e32 v18, 16, v13
	v_and_b32_e32 v19, 0xffff0000, v13
	v_lshlrev_b32_e32 v6, 16, v14
	v_and_b32_e32 v7, 0xffff0000, v14
	v_lshlrev_b32_e32 v22, 16, v15
	v_and_b32_e32 v23, 0xffff0000, v15
	s_waitcnt vmcnt(15)
	v_pk_add_f32 v[216:217], v[216:217], v[16:17]
	v_pk_add_f32 v[218:219], v[218:219], v[18:19]
	v_pk_add_f32 v[220:221], v[220:221], v[6:7]
	v_pk_add_f32 v[222:223], v[222:223], v[22:23]
	v_cvt_pk_bf16_f32 v216, v216, v217
	v_cvt_pk_bf16_f32 v217, v218, v219
	v_cvt_pk_bf16_f32 v218, v220, v221
	v_cvt_pk_bf16_f32 v219, v222, v223
	global_store_dwordx4 v[20:21], v[216:219], off
	s_add_i32 s23, s23, s33
	s_cmpk_gt_i32 s23, 0xff
	s_barrier
	s_cbranch_scc0 .LBB0_1002
